# idle CUs of each in-projection's 3rd round pre-run 1 chunk of the next up-proj-tail weight conversion (same routine/queue)
# speedup vs baseline: 1.0115x; 1.0073x over previous
.LBB0_710:
	s_waitcnt vmcnt(0)
	v_readlane_b32 s68, v253, 5
	s_barrier
	s_cmpk_lt_i32 s33, 206
	s_cbranch_scc1 .Lbrw_skip_L0
	s_and_b32 s100, s68, 0xffffffc0
	v_writelane_b32 v253, s100, 7
	s_lshl_b32 s100, s95, 6
	s_sub_i32 s100, 0, s100
	v_writelane_b32 v253, s100, 8
	s_nop 1
	v_readlane_b32 s100, v253, 7
	v_mbcnt_lo_u32_b32 v0, -1, 0
	v_mbcnt_hi_u32_b32 v0, -1, v0
	s_nop 1
	v_add_u32_e32 v0, s100, v0
	v_lshlrev_b32_e32 v0, 2, v0
	v_add_u32_e32 v0, 0x22400, v0
	v_writelane_b32 v255, s0, 0
	v_writelane_b32 v255, s1, 1
	v_writelane_b32 v255, s2, 2
	v_writelane_b32 v255, s3, 3
	v_writelane_b32 v255, s4, 4
	v_writelane_b32 v255, s5, 5
	v_writelane_b32 v255, s6, 6
	v_writelane_b32 v255, s7, 7
	v_writelane_b32 v255, s8, 8
	v_writelane_b32 v255, s9, 9
	v_writelane_b32 v255, s10, 10
	v_writelane_b32 v255, s11, 11
	v_writelane_b32 v255, s12, 12
	v_writelane_b32 v255, s13, 13
	v_writelane_b32 v255, s14, 14
	v_writelane_b32 v255, s15, 15
	v_writelane_b32 v255, s16, 16
	v_writelane_b32 v255, s17, 17
	v_writelane_b32 v255, s18, 18
	v_writelane_b32 v255, s19, 19
	v_writelane_b32 v255, s20, 20
	v_writelane_b32 v255, s21, 21
	v_writelane_b32 v255, s22, 22
	v_writelane_b32 v255, s23, 23
	v_writelane_b32 v255, s24, 24
	v_writelane_b32 v255, s25, 25
	v_writelane_b32 v255, s26, 26
	v_writelane_b32 v255, s27, 27
	v_writelane_b32 v255, s28, 28
	v_writelane_b32 v255, s29, 29
	v_writelane_b32 v255, s30, 30
	v_writelane_b32 v255, s31, 31
	v_writelane_b32 v255, s32, 32
	v_writelane_b32 v255, s33, 33
	v_writelane_b32 v255, s34, 34
	v_writelane_b32 v255, s35, 35
	v_writelane_b32 v255, s36, 36
	v_writelane_b32 v255, s37, 37
	v_writelane_b32 v255, s38, 38
	v_writelane_b32 v255, s39, 39
	v_writelane_b32 v255, s40, 40
	v_writelane_b32 v255, s41, 41
	v_writelane_b32 v255, s42, 42
	v_writelane_b32 v255, s43, 43
	v_writelane_b32 v255, s44, 44
	v_writelane_b32 v255, s45, 45
	v_writelane_b32 v255, s46, 46
	v_writelane_b32 v255, s47, 47
	v_writelane_b32 v255, s48, 48
	v_writelane_b32 v255, s49, 49
	v_writelane_b32 v255, s50, 50
	v_writelane_b32 v255, s51, 51
	v_writelane_b32 v255, s52, 52
	v_writelane_b32 v255, s53, 53
	v_writelane_b32 v255, s54, 54
	v_writelane_b32 v255, s55, 55
	v_writelane_b32 v255, s56, 56
	v_writelane_b32 v255, s57, 57
	v_writelane_b32 v255, s58, 58
	v_writelane_b32 v255, s59, 59
	v_writelane_b32 v255, s60, 60
	v_writelane_b32 v255, s61, 61
	v_writelane_b32 v255, s62, 62
	v_writelane_b32 v255, s63, 63
	ds_write_b32 v0, v255
	v_writelane_b32 v255, s64, 0
	v_writelane_b32 v255, s65, 1
	v_writelane_b32 v255, s66, 2
	v_writelane_b32 v255, s67, 3
	v_writelane_b32 v255, s68, 4
	v_writelane_b32 v255, s69, 5
	v_writelane_b32 v255, s70, 6
	v_writelane_b32 v255, s71, 7
	v_writelane_b32 v255, s72, 8
	v_writelane_b32 v255, s73, 9
	v_writelane_b32 v255, s74, 10
	v_writelane_b32 v255, s75, 11
	v_writelane_b32 v255, s76, 12
	v_writelane_b32 v255, s77, 13
	v_writelane_b32 v255, s78, 14
	v_writelane_b32 v255, s79, 15
	v_writelane_b32 v255, s80, 16
	v_writelane_b32 v255, s81, 17
	v_writelane_b32 v255, s82, 18
	v_writelane_b32 v255, s83, 19
	v_writelane_b32 v255, s84, 20
	v_writelane_b32 v255, s85, 21
	v_writelane_b32 v255, s86, 22
	v_writelane_b32 v255, s87, 23
	v_writelane_b32 v255, s88, 24
	v_writelane_b32 v255, s89, 25
	v_writelane_b32 v255, s90, 26
	v_writelane_b32 v255, s91, 27
	v_writelane_b32 v255, s92, 28
	v_writelane_b32 v255, s93, 29
	v_writelane_b32 v255, s94, 30
	v_writelane_b32 v255, s95, 31
	v_writelane_b32 v255, s96, 32
	v_writelane_b32 v255, s97, 33
	v_writelane_b32 v255, vcc_lo, 34
	v_writelane_b32 v255, vcc_hi, 35
	ds_write_b32 v0, v255 offset:2048
	s_waitcnt lgkmcnt(0)
	v_mov_b32_e32 v145, 0
	s_add_i32 s79, 0, 0x22040
	s_movk_i32 s80, 0x3000
	s_movk_i32 s81, 0xfff
	s_movk_i32 s82, 0x13ff
	s_movk_i32 s83, 0x23ff
	s_movk_i32 s84, 0x25ff
	s_add_i32 s85, 0, 0x22198
	s_add_i32 s86, 0, 0x22158
	s_add_i32 s87, 0, 0x22178
	s_add_i32 s88, 0, 0x221d8
	s_add_i32 s89, 0, 0x22160
	s_add_i32 s90, 0, 0x221a0
	s_add_i32 s91, 0, 0x221e0
	v_mov_b32_e32 v1, 0x221f0
	ds_read_b64 v[2:3], v1
	s_waitcnt lgkmcnt(0)
	v_readfirstlane_b32 s46, v2
	v_readfirstlane_b32 s47, v3
	s_mov_b32 s100, 1
	s_mov_b32 m0, 0x7fffffff
	s_branch .Lconv_entry_L0
.Lconv_ret_L0:
	s_mov_b64 exec, -1
	v_readlane_b32 s100, v253, 7
	v_mbcnt_lo_u32_b32 v0, -1, 0
	v_mbcnt_hi_u32_b32 v0, -1, v0
	s_nop 1
	v_add_u32_e32 v0, s100, v0
	v_lshlrev_b32_e32 v0, 2, v0
	v_add_u32_e32 v0, 0x22400, v0
	ds_read_b32 v255, v0 offset:2048
	s_waitcnt lgkmcnt(0)
	v_readlane_b32 s64, v255, 0
	v_readlane_b32 s65, v255, 1
	v_readlane_b32 s66, v255, 2
	v_readlane_b32 s67, v255, 3
	v_readlane_b32 s68, v255, 4
	v_readlane_b32 s69, v255, 5
	v_readlane_b32 s70, v255, 6
	v_readlane_b32 s71, v255, 7
	v_readlane_b32 s72, v255, 8
	v_readlane_b32 s73, v255, 9
	v_readlane_b32 s74, v255, 10
	v_readlane_b32 s75, v255, 11
	v_readlane_b32 s76, v255, 12
	v_readlane_b32 s77, v255, 13
	v_readlane_b32 s78, v255, 14
	v_readlane_b32 s79, v255, 15
	v_readlane_b32 s80, v255, 16
	v_readlane_b32 s81, v255, 17
	v_readlane_b32 s82, v255, 18
	v_readlane_b32 s83, v255, 19
	v_readlane_b32 s84, v255, 20
	v_readlane_b32 s85, v255, 21
	v_readlane_b32 s86, v255, 22
	v_readlane_b32 s87, v255, 23
	v_readlane_b32 s88, v255, 24
	v_readlane_b32 s89, v255, 25
	v_readlane_b32 s90, v255, 26
	v_readlane_b32 s91, v255, 27
	v_readlane_b32 s92, v255, 28
	v_readlane_b32 s93, v255, 29
	v_readlane_b32 s94, v255, 30
	v_readlane_b32 s95, v255, 31
	v_readlane_b32 s96, v255, 32
	v_readlane_b32 s97, v255, 33
	v_readlane_b32 vcc_lo, v255, 34
	v_readlane_b32 vcc_hi, v255, 35
	ds_read_b32 v255, v0
	s_waitcnt lgkmcnt(0)
	v_readlane_b32 s0, v255, 0
	v_readlane_b32 s1, v255, 1
	v_readlane_b32 s2, v255, 2
	v_readlane_b32 s3, v255, 3
	v_readlane_b32 s4, v255, 4
	v_readlane_b32 s5, v255, 5
	v_readlane_b32 s6, v255, 6
	v_readlane_b32 s7, v255, 7
	v_readlane_b32 s8, v255, 8
	v_readlane_b32 s9, v255, 9
	v_readlane_b32 s10, v255, 10
	v_readlane_b32 s11, v255, 11
	v_readlane_b32 s12, v255, 12
	v_readlane_b32 s13, v255, 13
	v_readlane_b32 s14, v255, 14
	v_readlane_b32 s15, v255, 15
	v_readlane_b32 s16, v255, 16
	v_readlane_b32 s17, v255, 17
	v_readlane_b32 s18, v255, 18
	v_readlane_b32 s19, v255, 19
	v_readlane_b32 s20, v255, 20
	v_readlane_b32 s21, v255, 21
	v_readlane_b32 s22, v255, 22
	v_readlane_b32 s23, v255, 23
	v_readlane_b32 s24, v255, 24
	v_readlane_b32 s25, v255, 25
	v_readlane_b32 s26, v255, 26
	v_readlane_b32 s27, v255, 27
	v_readlane_b32 s28, v255, 28
	v_readlane_b32 s29, v255, 29
	v_readlane_b32 s30, v255, 30
	v_readlane_b32 s31, v255, 31
	v_readlane_b32 s32, v255, 32
	v_readlane_b32 s33, v255, 33
	v_readlane_b32 s34, v255, 34
	v_readlane_b32 s35, v255, 35
	v_readlane_b32 s36, v255, 36
	v_readlane_b32 s37, v255, 37
	v_readlane_b32 s38, v255, 38
	v_readlane_b32 s39, v255, 39
	v_readlane_b32 s40, v255, 40
	v_readlane_b32 s41, v255, 41
	v_readlane_b32 s42, v255, 42
	v_readlane_b32 s43, v255, 43
	v_readlane_b32 s44, v255, 44
	v_readlane_b32 s45, v255, 45
	v_readlane_b32 s46, v255, 46
	v_readlane_b32 s47, v255, 47
	v_readlane_b32 s48, v255, 48
	v_readlane_b32 s49, v255, 49
	v_readlane_b32 s50, v255, 50
	v_readlane_b32 s51, v255, 51
	v_readlane_b32 s52, v255, 52
	v_readlane_b32 s53, v255, 53
	v_readlane_b32 s54, v255, 54
	v_readlane_b32 s55, v255, 55
	v_readlane_b32 s56, v255, 56
	v_readlane_b32 s57, v255, 57
	v_readlane_b32 s58, v255, 58
	v_readlane_b32 s59, v255, 59
	v_readlane_b32 s60, v255, 60
	v_readlane_b32 s61, v255, 61
	v_readlane_b32 s62, v255, 62
	v_readlane_b32 s63, v255, 63
	s_mov_b32 m0, 0
	s_nop 4
.Lbrw_skip_L0:
.LBB0_711:
	v_readlane_b32 s4, v253, 3
	v_readlane_b32 s5, v253, 4
	s_cmp_lt_i32 s5, 3
	s_cbranch_scc1 .LBB0_765
	s_waitcnt vmcnt(0)
	s_lshl_b32 s0, s95, 6
	s_sub_i32 s0, 0, s0
	s_waitcnt lgkmcnt(0)
	s_barrier
	v_mbcnt_lo_u32_b32 v0, -1, 0
	v_mbcnt_hi_u32_b32 v0, -1, v0
	s_nop 0
	v_cmp_eq_u32_e32 vcc, s0, v0
	s_and_saveexec_b64 s[0:1], vcc
	s_cbranch_execz .LBB0_764
	s_add_i32 s2, 0, 0x22020
	v_mov_b32_e32 v0, s2
	s_waitcnt vmcnt(0) expcnt(0) lgkmcnt(0)
	ds_read_b32 v2, v0
	s_add_i32 s2, 0, 0x22024
	v_mov_b32_e32 v0, s2
	ds_read_b32 v0, v0
	s_waitcnt lgkmcnt(1)
	v_cmp_ne_u32_e32 vcc, 0, v2
	s_cbranch_vccnz .LBB0_728
	v_readlane_b32 s2, v253, 0
	v_readlane_b32 s3, v253, 1
	s_load_dwordx2 s[6:7], s[2:3], 0x4
	s_add_u32 s2, s50, 0x4200
	s_addc_u32 s3, s51, 0
	s_add_u32 s4, s50, 0x4400
	s_addc_u32 s5, s51, 0
	s_waitcnt lgkmcnt(0)
	s_mul_i32 s25, s6, s24
	s_add_u32 s6, s50, 0x4500
	s_mul_i32 s25, s25, s7
	s_addc_u32 s7, s51, 0
	s_add_u32 s8, s50, 0x4600
	s_addc_u32 s9, s51, 0
	s_add_u32 s10, s50, 0x4700
	s_addc_u32 s11, s51, 0
	s_add_u32 s12, s50, 0x4800
	s_addc_u32 s13, s51, 0
	s_add_u32 s14, s50, 0x4900
	s_addc_u32 s15, s51, 0
	s_add_u32 s16, s50, 0x4a00
	s_addc_u32 s17, s51, 0
	s_add_u32 s18, s50, 0x4b00
	s_addc_u32 s19, s51, 0
	s_add_u32 s20, s50, 0x4c00
	s_addc_u32 s21, s51, 0
	s_add_u32 s22, s50, 0x4d00
	s_addc_u32 s23, s51, 0
	s_add_u32 s26, s50, 0x4e00
	s_addc_u32 s27, s51, 0
	s_add_u32 s28, s50, 0x4f00
	s_addc_u32 s29, s51, 0
	s_add_u32 s30, s50, 0x5000
	s_addc_u32 s31, s51, 0
	s_add_u32 s34, s50, 0x5100
	s_addc_u32 s35, s51, 0
	s_add_u32 s36, s50, 0x5200
	s_addc_u32 s37, s51, 0
	s_add_u32 s38, s50, 0x5300
	s_addc_u32 s39, s51, 0
	s_mov_b32 s46, 1
	v_mov_b32_e32 v16, 0
	s_branch .LBB0_716

.LBB0_1788:
.Lconv_entry_L0:
	s_add_u32 s36, s46, 0x14100
	s_addc_u32 s37, s47, 0
	s_add_u32 s38, s46, 0x1700000
	s_addc_u32 s39, s47, 0
	s_add_u32 s48, s46, 0x17a00000
	s_addc_u32 s49, s47, 0
	v_readlane_b32 s0, v253, 7
	s_add_u32 s50, s46, 0x9600000
	v_mbcnt_lo_u32_b32 v0, -1, 0
	v_mbcnt_hi_u32_b32 v0, -1, v0
	s_addc_u32 s51, s47, 0
	v_add_u32_e32 v2, s0, v0
	s_waitcnt lgkmcnt(0)
	v_and_b32_e32 v1, 63, v0
	v_ashrrev_i32_e32 v2, 6, v2
	s_movk_i32 s0, 0x4100
	s_add_u32 s52, s46, 0x5e00000
	v_bfe_u32 v158, v0, 3, 3
	v_lshlrev_b32_e32 v0, 3, v0
	v_mul_lo_u32 v3, v2, s0
	s_addc_u32 s53, s47, 0
	v_and_b32_e32 v0, 56, v0
	v_add_u32_e32 v3, 0, v3
	v_lshlrev_b32_e32 v156, 3, v2
	s_add_u32 s54, s46, 0xf600000
	v_mul_u32_u24_e32 v2, 0x104, v0
	v_lshlrev_b32_e32 v4, 2, v158
	s_addc_u32 s55, s47, 0
	v_lshl_add_u32 v157, v1, 2, v3
	v_add3_u32 v159, v3, v2, v4
	v_or_b32_e32 v160, 8, v158
	v_or_b32_e32 v161, 16, v158
	v_or_b32_e32 v162, 24, v158
	v_or_b32_e32 v163, 32, v158
	v_or_b32_e32 v167, 40, v158
	v_or_b32_e32 v168, 48, v158
	v_or_b32_e32 v169, 56, v158
	s_branch .LBB0_1791

.LBB0_1791:
	s_cmp_eq_u32 m0, 0x7fffffff
	s_cbranch_scc0 .Lconv_go_L0
	s_cmp_eq_u32 s100, 0
	s_cbranch_scc1 .LBB0_1910
	s_sub_u32 s100, s100, 1

.LBB0_1910:
	s_cmp_eq_u32 m0, 0x7fffffff
	s_cbranch_scc1 .Lconv_ret_L0
	s_branch .LBB0_2033

.LBB0_2205:
	s_waitcnt vmcnt(0)
	s_barrier
	s_cmpk_lt_i32 s33, 172
	s_cbranch_scc1 .Lbrw_skip_L1
	v_readlane_b32 s100, v253, 7
	v_mbcnt_lo_u32_b32 v0, -1, 0
	v_mbcnt_hi_u32_b32 v0, -1, v0
	s_nop 1
	v_add_u32_e32 v0, s100, v0
	v_lshlrev_b32_e32 v0, 2, v0
	v_add_u32_e32 v0, 0x22400, v0
	v_writelane_b32 v255, s0, 0
	v_writelane_b32 v255, s1, 1
	v_writelane_b32 v255, s2, 2
	v_writelane_b32 v255, s3, 3
	v_writelane_b32 v255, s4, 4
	v_writelane_b32 v255, s5, 5
	v_writelane_b32 v255, s6, 6
	v_writelane_b32 v255, s7, 7
	v_writelane_b32 v255, s8, 8
	v_writelane_b32 v255, s9, 9
	v_writelane_b32 v255, s10, 10
	v_writelane_b32 v255, s11, 11
	v_writelane_b32 v255, s12, 12
	v_writelane_b32 v255, s13, 13
	v_writelane_b32 v255, s14, 14
	v_writelane_b32 v255, s15, 15
	v_writelane_b32 v255, s16, 16
	v_writelane_b32 v255, s17, 17
	v_writelane_b32 v255, s18, 18
	v_writelane_b32 v255, s19, 19
	v_writelane_b32 v255, s20, 20
	v_writelane_b32 v255, s21, 21
	v_writelane_b32 v255, s22, 22
	v_writelane_b32 v255, s23, 23
	v_writelane_b32 v255, s24, 24
	v_writelane_b32 v255, s25, 25
	v_writelane_b32 v255, s26, 26
	v_writelane_b32 v255, s27, 27
	v_writelane_b32 v255, s28, 28
	v_writelane_b32 v255, s29, 29
	v_writelane_b32 v255, s30, 30
	v_writelane_b32 v255, s31, 31
	v_writelane_b32 v255, s32, 32
	v_writelane_b32 v255, s33, 33
	v_writelane_b32 v255, s34, 34
	v_writelane_b32 v255, s35, 35
	v_writelane_b32 v255, s36, 36
	v_writelane_b32 v255, s37, 37
	v_writelane_b32 v255, s38, 38
	v_writelane_b32 v255, s39, 39
	v_writelane_b32 v255, s40, 40
	v_writelane_b32 v255, s41, 41
	v_writelane_b32 v255, s42, 42
	v_writelane_b32 v255, s43, 43
	v_writelane_b32 v255, s44, 44
	v_writelane_b32 v255, s45, 45
	v_writelane_b32 v255, s46, 46
	v_writelane_b32 v255, s47, 47
	v_writelane_b32 v255, s48, 48
	v_writelane_b32 v255, s49, 49
	v_writelane_b32 v255, s50, 50
	v_writelane_b32 v255, s51, 51
	v_writelane_b32 v255, s52, 52
	v_writelane_b32 v255, s53, 53
	v_writelane_b32 v255, s54, 54
	v_writelane_b32 v255, s55, 55
	v_writelane_b32 v255, s56, 56
	v_writelane_b32 v255, s57, 57
	v_writelane_b32 v255, s58, 58
	v_writelane_b32 v255, s59, 59
	v_writelane_b32 v255, s60, 60
	v_writelane_b32 v255, s61, 61
	v_writelane_b32 v255, s62, 62
	v_writelane_b32 v255, s63, 63
	ds_write_b32 v0, v255
	v_writelane_b32 v255, s64, 0
	v_writelane_b32 v255, s65, 1
	v_writelane_b32 v255, s66, 2
	v_writelane_b32 v255, s67, 3
	v_writelane_b32 v255, s68, 4
	v_writelane_b32 v255, s69, 5
	v_writelane_b32 v255, s70, 6
	v_writelane_b32 v255, s71, 7
	v_writelane_b32 v255, s72, 8
	v_writelane_b32 v255, s73, 9
	v_writelane_b32 v255, s74, 10
	v_writelane_b32 v255, s75, 11
	v_writelane_b32 v255, s76, 12
	v_writelane_b32 v255, s77, 13
	v_writelane_b32 v255, s78, 14
	v_writelane_b32 v255, s79, 15
	v_writelane_b32 v255, s80, 16
	v_writelane_b32 v255, s81, 17
	v_writelane_b32 v255, s82, 18
	v_writelane_b32 v255, s83, 19
	v_writelane_b32 v255, s84, 20
	v_writelane_b32 v255, s85, 21
	v_writelane_b32 v255, s86, 22
	v_writelane_b32 v255, s87, 23
	v_writelane_b32 v255, s88, 24
	v_writelane_b32 v255, s89, 25
	v_writelane_b32 v255, s90, 26
	v_writelane_b32 v255, s91, 27
	v_writelane_b32 v255, s92, 28
	v_writelane_b32 v255, s93, 29
	v_writelane_b32 v255, s94, 30
	v_writelane_b32 v255, s95, 31
	v_writelane_b32 v255, s96, 32
	v_writelane_b32 v255, s97, 33
	v_writelane_b32 v255, vcc_lo, 34
	v_writelane_b32 v255, vcc_hi, 35
	ds_write_b32 v0, v255 offset:2048
	s_waitcnt lgkmcnt(0)
	v_mov_b32_e32 v145, 0
	s_add_i32 s76, 0, 0x22040
	s_movk_i32 s77, 0x3080
	s_movk_i32 s78, 0xfff
	s_movk_i32 s79, 0x13ff
	s_movk_i32 s80, 0x23ff
	s_movk_i32 s81, 0x25ff
	s_add_i32 s82, 0, 0x221a8
	s_add_i32 s83, 0, 0x22158
	s_add_i32 s84, 0, 0x22178
	s_add_i32 s85, 0, 0x221d8
	s_add_i32 s86, 0, 0x22160
	s_add_i32 s87, 0, 0x221d0
	s_add_i32 s88, 0, 0x221e0
	s_movk_i32 s89, 0x11ff
	s_movk_i32 s90, 0x120f
	s_movk_i32 s91, 0x120b
	v_mov_b32_e32 v1, 0x221f0
	ds_read_b64 v[2:3], v1
	s_waitcnt lgkmcnt(0)
	v_readfirstlane_b32 s44, v2
	v_readfirstlane_b32 s45, v3
	s_mov_b32 s100, 1
	s_mov_b32 m0, 0x7fffffff
	s_branch .Lconv_entry_L1

.Lbrw_skip_L1:
.LBB0_2206:
	v_readlane_b32 s4, v253, 3
	v_readlane_b32 s5, v253, 4
	s_cmp_lt_i32 s5, 12
	s_cbranch_scc1 .LBB0_2260
	s_waitcnt vmcnt(0)
	v_readlane_b32 s0, v253, 8
	s_waitcnt lgkmcnt(0)
	s_barrier
	v_mbcnt_lo_u32_b32 v0, -1, 0
	v_mbcnt_hi_u32_b32 v0, -1, v0
	s_nop 0
	v_cmp_eq_u32_e32 vcc, s0, v0
	s_and_saveexec_b64 s[0:1], vcc
	s_cbranch_execz .LBB0_2259
	s_add_i32 s2, 0, 0x22020
	v_mov_b32_e32 v0, s2
	s_waitcnt vmcnt(0) expcnt(0) lgkmcnt(0)
	ds_read_b32 v2, v0
	s_add_i32 s2, 0, 0x22024
	v_mov_b32_e32 v0, s2
	ds_read_b32 v0, v0
	s_waitcnt lgkmcnt(1)
	v_cmp_ne_u32_e32 vcc, 0, v2
	s_cbranch_vccnz .LBB0_2223
	v_readlane_b32 s4, v253, 0
	v_readlane_b32 s5, v253, 1
	s_load_dwordx2 s[2:3], s[4:5], 0x4
	v_mov_b32_e32 v16, 0
	s_waitcnt lgkmcnt(0)
	s_mul_i32 s2, s2, s24
	s_mul_i32 s2, s2, s3
	s_mov_b32 s3, 1
	s_branch .LBB0_2211

.LBB0_3152:
.Lconv_entry_L1:
	s_add_u32 s36, s44, 0x14200
	s_addc_u32 s37, s45, 0
	s_add_u32 s38, s44, 0x2c00000
	s_addc_u32 s39, s45, 0
	s_add_u32 s46, s44, 0x17e00000
	s_addc_u32 s47, s45, 0
	v_readlane_b32 s0, v253, 7
	s_add_u32 s48, s44, 0xb600000
	v_mbcnt_lo_u32_b32 v0, -1, 0
	v_mbcnt_hi_u32_b32 v0, -1, v0
	s_addc_u32 s49, s45, 0
	s_waitcnt lgkmcnt(0)
	v_add_u32_e32 v1, s0, v0
	v_and_b32_e32 v5, 63, v0
	v_ashrrev_i32_e32 v1, 6, v1
	s_movk_i32 s0, 0x4100
	s_add_u32 s50, s44, 0x6600000
	v_bfe_u32 v162, v0, 3, 3
	v_lshlrev_b32_e32 v0, 3, v0
	v_mul_lo_u32 v2, v1, s0
	s_addc_u32 s51, s45, 0
	v_and_b32_e32 v4, 56, v0
	v_add_u32_e32 v2, 0, v2
	v_lshlrev_b32_e32 v160, 3, v1
	s_add_u32 s52, s44, 0x11600000
	v_mul_u32_u24_e32 v0, 0x104, v4
	v_lshlrev_b32_e32 v1, 2, v162
	s_addc_u32 s53, s45, 0
	v_lshl_add_u32 v161, v5, 2, v2
	v_add3_u32 v163, v2, v0, v1
	v_or_b32_e32 v167, 8, v162
	v_or_b32_e32 v168, 16, v162
	v_or_b32_e32 v169, 24, v162
	v_or_b32_e32 v170, 32, v162
	v_or_b32_e32 v171, 40, v162
	v_or_b32_e32 v172, 48, v162
	v_or_b32_e32 v173, 56, v162
	s_branch .LBB0_3155

.LBB0_3773:
	s_waitcnt vmcnt(0)
	s_barrier
	s_cmpk_lt_i32 s33, 206
	s_cbranch_scc1 .Lbrw_skip_L2
	v_readlane_b32 s100, v253, 7
	v_mbcnt_lo_u32_b32 v0, -1, 0
	v_mbcnt_hi_u32_b32 v0, -1, v0
	s_nop 1
	v_add_u32_e32 v0, s100, v0
	v_lshlrev_b32_e32 v0, 2, v0
	v_add_u32_e32 v0, 0x22400, v0
	v_writelane_b32 v255, s0, 0
	v_writelane_b32 v255, s1, 1
	v_writelane_b32 v255, s2, 2
	v_writelane_b32 v255, s3, 3
	v_writelane_b32 v255, s4, 4
	v_writelane_b32 v255, s5, 5
	v_writelane_b32 v255, s6, 6
	v_writelane_b32 v255, s7, 7
	v_writelane_b32 v255, s8, 8
	v_writelane_b32 v255, s9, 9
	v_writelane_b32 v255, s10, 10
	v_writelane_b32 v255, s11, 11
	v_writelane_b32 v255, s12, 12
	v_writelane_b32 v255, s13, 13
	v_writelane_b32 v255, s14, 14
	v_writelane_b32 v255, s15, 15
	v_writelane_b32 v255, s16, 16
	v_writelane_b32 v255, s17, 17
	v_writelane_b32 v255, s18, 18
	v_writelane_b32 v255, s19, 19
	v_writelane_b32 v255, s20, 20
	v_writelane_b32 v255, s21, 21
	v_writelane_b32 v255, s22, 22
	v_writelane_b32 v255, s23, 23
	v_writelane_b32 v255, s24, 24
	v_writelane_b32 v255, s25, 25
	v_writelane_b32 v255, s26, 26
	v_writelane_b32 v255, s27, 27
	v_writelane_b32 v255, s28, 28
	v_writelane_b32 v255, s29, 29
	v_writelane_b32 v255, s30, 30
	v_writelane_b32 v255, s31, 31
	v_writelane_b32 v255, s32, 32
	v_writelane_b32 v255, s33, 33
	v_writelane_b32 v255, s34, 34
	v_writelane_b32 v255, s35, 35
	v_writelane_b32 v255, s36, 36
	v_writelane_b32 v255, s37, 37
	v_writelane_b32 v255, s38, 38
	v_writelane_b32 v255, s39, 39
	v_writelane_b32 v255, s40, 40
	v_writelane_b32 v255, s41, 41
	v_writelane_b32 v255, s42, 42
	v_writelane_b32 v255, s43, 43
	v_writelane_b32 v255, s44, 44
	v_writelane_b32 v255, s45, 45
	v_writelane_b32 v255, s46, 46
	v_writelane_b32 v255, s47, 47
	v_writelane_b32 v255, s48, 48
	v_writelane_b32 v255, s49, 49
	v_writelane_b32 v255, s50, 50
	v_writelane_b32 v255, s51, 51
	v_writelane_b32 v255, s52, 52
	v_writelane_b32 v255, s53, 53
	v_writelane_b32 v255, s54, 54
	v_writelane_b32 v255, s55, 55
	v_writelane_b32 v255, s56, 56
	v_writelane_b32 v255, s57, 57
	v_writelane_b32 v255, s58, 58
	v_writelane_b32 v255, s59, 59
	v_writelane_b32 v255, s60, 60
	v_writelane_b32 v255, s61, 61
	v_writelane_b32 v255, s62, 62
	v_writelane_b32 v255, s63, 63
	ds_write_b32 v0, v255
	v_writelane_b32 v255, s64, 0
	v_writelane_b32 v255, s65, 1
	v_writelane_b32 v255, s66, 2
	v_writelane_b32 v255, s67, 3
	v_writelane_b32 v255, s68, 4
	v_writelane_b32 v255, s69, 5
	v_writelane_b32 v255, s70, 6
	v_writelane_b32 v255, s71, 7
	v_writelane_b32 v255, s72, 8
	v_writelane_b32 v255, s73, 9
	v_writelane_b32 v255, s74, 10
	v_writelane_b32 v255, s75, 11
	v_writelane_b32 v255, s76, 12
	v_writelane_b32 v255, s77, 13
	v_writelane_b32 v255, s78, 14
	v_writelane_b32 v255, s79, 15
	v_writelane_b32 v255, s80, 16
	v_writelane_b32 v255, s81, 17
	v_writelane_b32 v255, s82, 18
	v_writelane_b32 v255, s83, 19
	v_writelane_b32 v255, s84, 20
	v_writelane_b32 v255, s85, 21
	v_writelane_b32 v255, s86, 22
	v_writelane_b32 v255, s87, 23
	v_writelane_b32 v255, s88, 24
	v_writelane_b32 v255, s89, 25
	v_writelane_b32 v255, s90, 26
	v_writelane_b32 v255, s91, 27
	v_writelane_b32 v255, s92, 28
	v_writelane_b32 v255, s93, 29
	v_writelane_b32 v255, s94, 30
	v_writelane_b32 v255, s95, 31
	v_writelane_b32 v255, s96, 32
	v_writelane_b32 v255, s97, 33
	v_writelane_b32 v255, vcc_lo, 34
	v_writelane_b32 v255, vcc_hi, 35
	ds_write_b32 v0, v255 offset:2048
	s_waitcnt lgkmcnt(0)
	v_mov_b32_e32 v145, 0
	s_add_i32 s76, 0, 0x22040
	s_movk_i32 s77, 0x3080
	s_movk_i32 s78, 0xfff
	s_movk_i32 s79, 0x13ff
	s_movk_i32 s80, 0x23ff
	s_movk_i32 s81, 0x25ff
	s_add_i32 s82, 0, 0x22180
	s_add_i32 s83, 0, 0x22158
	s_add_i32 s84, 0, 0x22178
	s_add_i32 s85, 0, 0x221d8
	s_add_i32 s86, 0, 0x22160
	s_add_i32 s87, 0, 0x22190
	s_add_i32 s88, 0, 0x221e0
	s_movk_i32 s89, 0x11ff
	s_movk_i32 s90, 0x120f
	s_movk_i32 s91, 0x120b
	v_mov_b32_e32 v1, 0x221f0
	ds_read_b64 v[2:3], v1
	s_waitcnt lgkmcnt(0)
	v_readfirstlane_b32 s44, v2
	v_readfirstlane_b32 s45, v3
	s_mov_b32 s100, 1
	s_mov_b32 m0, 0x7fffffff
	s_branch .Ltramp_fwd_L2

.Lbrw_skip_L2:
.LBB0_3774:
	v_readlane_b32 s6, v253, 3
	v_readlane_b32 s7, v253, 4
	s_cmp_lt_i32 s7, 21
	s_cbranch_scc1 .LBB0_3828
	s_waitcnt vmcnt(0)
	v_readlane_b32 s0, v253, 8
	s_waitcnt lgkmcnt(0)
	s_barrier
	v_mbcnt_lo_u32_b32 v0, -1, 0
	v_mbcnt_hi_u32_b32 v0, -1, v0
	s_nop 0
	v_cmp_eq_u32_e32 vcc, s0, v0
	s_and_saveexec_b64 s[0:1], vcc
	s_cbranch_execz .LBB0_3827
	s_add_i32 s2, 0, 0x22020
	v_mov_b32_e32 v0, s2
	s_waitcnt vmcnt(0) expcnt(0) lgkmcnt(0)
	ds_read_b32 v2, v0
	s_add_i32 s2, 0, 0x22024
	v_mov_b32_e32 v0, s2
	ds_read_b32 v0, v0
	s_waitcnt lgkmcnt(1)
	v_cmp_ne_u32_e32 vcc, 0, v2
	s_cbranch_vccnz .LBB0_3791
	v_readlane_b32 s4, v253, 0
	v_readlane_b32 s5, v253, 1
	s_load_dwordx2 s[2:3], s[4:5], 0x4
	v_mov_b32_e32 v16, 0
	s_waitcnt lgkmcnt(0)
	s_mul_i32 s2, s2, s24
	s_mul_i32 s2, s2, s3
	s_mov_b32 s3, 1
	s_branch .LBB0_3779

.LBB0_4991:
	s_or_b64 exec, exec, s[0:1]
	global_load_ushort v2, v[2:3], off offset:512
	s_waitcnt vmcnt(0)
	v_lshlrev_b32_e32 v2, 16, v2
	global_load_dword v3, v[50:51], off offset:1024
	s_waitcnt vmcnt(0)
	v_add_f32_e32 v2, v3, v2
	v_mul_f32_e32 v3, 0xbfb8aa3b, v2
	v_exp_f32_e32 v3, v3
	s_nop 0
	v_add_f32_e32 v3, 1.0, v3
	v_div_scale_f32 v5, s[0:1], v3, v3, v2
	s_waitcnt lgkmcnt(0)
	v_rcp_f32_e32 v6, v5
	s_nop 0
	v_fma_f32 v7, -v5, v6, 1.0
	v_fmac_f32_e32 v6, v7, v6
	v_div_scale_f32 v7, vcc, v2, v3, v2
	v_mul_f32_e32 v8, v7, v6
	v_fma_f32 v9, -v5, v8, v7
	v_fmac_f32_e32 v8, v9, v6
	v_fma_f32 v5, -v5, v8, v7
	v_div_fmas_f32 v5, v5, v6, v8
	v_div_fixup_f32 v2, v5, v3, v2
	v_mul_f32_e32 v3, v47, v4
	global_load_dword v4, v[48:49], off offset:1024
	s_waitcnt vmcnt(0)
	v_mul_f32_e32 v3, v3, v4
	v_mul_f32_e32 v2, v3, v2
	ds_bpermute_b32 v3, v58, v2
	s_and_saveexec_b64 s[0:1], s[34:35]
	s_cbranch_execz .LBB0_4791
	s_waitcnt lgkmcnt(0)
	v_cvt_pk_bf16_f32 v2, v2, v3
	global_store_dword v[0:1], v2, off offset:512
	s_branch .LBB0_4791
.Ltramp_fwd_L2:
	s_branch .Lconv_entry_L2
.Ltramp_back_L2:
	s_branch .Lconv_ret_L2
.LBB0_4993:
	s_and_b64 vcc, exec, s[42:43]
	s_cbranch_vccz .LBB0_5604
	s_add_i32 s0, 0, 0x221f0
	v_mov_b32_e32 v0, s0
	ds_read_b64 v[0:1], v0
	v_readlane_b32 s0, v253, 2
	s_mov_b32 s43, 0
	s_waitcnt lgkmcnt(0)
	v_readfirstlane_b32 s3, v0
	v_readfirstlane_b32 s2, v1
	s_add_u32 s76, s3, 0x439c6000
	s_addc_u32 s77, s2, 0
	s_cmp_lt_i32 s0, 32
	s_cselect_b64 s[40:41], -1, 0
	s_cmp_gt_i32 s0, 31
	s_cbranch_scc1 .LBB0_5234
	s_add_u32 s4, s3, 0x1ec00000
	s_addc_u32 s5, s2, 0
	s_add_u32 s6, s3, 0x24540000
	s_addc_u32 s7, s2, 0
	s_add_u32 s8, s3, 0x1ec00c00
	s_addc_u32 s9, s2, 0
	s_add_u32 s10, s3, 0x1ec01800
	s_addc_u32 s11, s2, 0
	s_add_u32 s12, s3, 0x10000
	s_addc_u32 s13, s2, 0
	s_add_u32 s29, s3, 0xc000
	s_addc_u32 s30, s2, 0
	s_add_u32 s31, s3, 0x429a6000
	s_addc_u32 s45, s2, 0
	s_add_u32 s62, s3, 0x42ba6000
	s_addc_u32 s63, s2, 0
	s_movk_i32 s64, 0x2a00
	s_add_i32 s65, 0, 0x22140
	s_mov_b32 s66, 0xbfb8aa3b
	s_mov_b32 s67, 0x800000
	s_mov_b32 s68, 0x3f317217
	s_mov_b32 s69, 0x7f800000
	s_add_i32 s70, 0, 0x20824
	v_mov_b32_e32 v1, 0
	s_add_i32 s71, 0, 0x20804
	s_add_i32 s72, 0, 0x20808
	s_add_i32 s73, 0, 0x2080c
	s_add_i32 s74, 0, 0x20810
	s_add_i32 s75, 0, 0x20814
	s_add_i32 s78, 0, 0x20818
	s_add_i32 s79, 0, 0x2081c
	s_mov_b32 s44, 0x413504f3
	s_add_i32 s80, 0, 0x10800
	s_add_i32 s81, 0, 0x20820
	s_add_i32 s82, 0, 0x20828
	s_add_i32 s83, 0, 0x20838
	v_mov_b32_e32 v202, 0x260
	s_brev_b32 s84, -3
	v_mov_b32_e32 v203, 0x41b17218
	v_mov_b32_e32 v205, 0xff800000
	v_mov_b32_e32 v206, 0x1000
	v_mov_b32_e32 v207, 0x2000
	v_mov_b32_e32 v208, 0x3000
	v_mov_b32_e32 v209, 0x8000
	v_mov_b32_e32 v210, 0x9000
	v_mov_b32_e32 v211, 0xa000
	v_mov_b32_e32 v212, 0xb000
	v_mov_b32_e32 v213, 0x10000
	v_mov_b32_e32 v214, 0x11000
	v_mov_b32_e32 v215, 0x12000
	v_mov_b32_e32 v216, 0x13000
	v_mov_b32_e32 v217, 0x18000
	v_mov_b32_e32 v218, 0x19000
	v_mov_b32_e32 v219, 0x1a000
	v_mov_b32_e32 v220, 0x1b000
	v_readlane_b32 s85, v253, 2
	s_branch .LBB0_4998

.LBB0_5725:
.Lconv_entry_L2:
	s_add_u32 s36, s44, 0x14300
	s_addc_u32 s37, s45, 0
	s_add_u32 s38, s44, 0x4100000
	s_addc_u32 s39, s45, 0
	s_add_u32 s46, s44, 0x18200000
	s_addc_u32 s47, s45, 0
	v_readlane_b32 s0, v253, 7
	s_add_u32 s48, s44, 0xd600000
	v_mbcnt_lo_u32_b32 v0, -1, 0
	v_mbcnt_hi_u32_b32 v0, -1, v0
	s_addc_u32 s49, s45, 0
	s_waitcnt lgkmcnt(0)
	v_add_u32_e32 v1, s0, v0
	v_and_b32_e32 v5, 63, v0
	v_ashrrev_i32_e32 v1, 6, v1
	s_movk_i32 s0, 0x4100
	s_add_u32 s50, s44, 0x6e00000
	v_bfe_u32 v162, v0, 3, 3
	v_lshlrev_b32_e32 v0, 3, v0
	v_mul_lo_u32 v2, v1, s0
	s_addc_u32 s51, s45, 0
	v_and_b32_e32 v4, 56, v0
	v_add_u32_e32 v2, 0, v2
	v_lshlrev_b32_e32 v160, 3, v1
	s_add_u32 s52, s44, 0x13600000
	v_mul_u32_u24_e32 v0, 0x104, v4
	v_lshlrev_b32_e32 v1, 2, v162
	s_addc_u32 s53, s45, 0
	v_lshl_add_u32 v161, v5, 2, v2
	v_add3_u32 v163, v2, v0, v1
	v_or_b32_e32 v167, 8, v162
	v_or_b32_e32 v168, 16, v162
	v_or_b32_e32 v169, 24, v162
	v_or_b32_e32 v170, 32, v162
	v_or_b32_e32 v171, 40, v162
	v_or_b32_e32 v172, 48, v162
	v_or_b32_e32 v173, 56, v162
	s_branch .LBB0_5728

	.amdhsa_kernel _Z9trunk_fwd4Args
		.amdhsa_group_segment_fixed_size 0
		.amdhsa_private_segment_fixed_size 0
		.amdhsa_kernarg_size 512
		.amdhsa_user_sgpr_count 2
		.amdhsa_user_sgpr_dispatch_ptr 0
		.amdhsa_user_sgpr_queue_ptr 0
		.amdhsa_user_sgpr_kernarg_segment_ptr 1
		.amdhsa_user_sgpr_dispatch_id 0
		.amdhsa_user_sgpr_kernarg_preload_length 0
		.amdhsa_user_sgpr_kernarg_preload_offset 0
		.amdhsa_user_sgpr_private_segment_size 0
		.amdhsa_uses_dynamic_stack 0
		.amdhsa_enable_private_segment 0
		.amdhsa_system_sgpr_workgroup_id_x 1
		.amdhsa_system_sgpr_workgroup_id_y 0
		.amdhsa_system_sgpr_workgroup_id_z 0
		.amdhsa_system_sgpr_workgroup_info 0
		.amdhsa_system_vgpr_workitem_id 0
		.amdhsa_next_free_vgpr 256
		.amdhsa_next_free_sgpr 102
		.amdhsa_accum_offset 256
		.amdhsa_reserve_vcc 1
		.amdhsa_float_round_mode_32 0
		.amdhsa_float_round_mode_16_64 0
		.amdhsa_float_denorm_mode_32 3
		.amdhsa_float_denorm_mode_16_64 3
		.amdhsa_dx10_clamp 1
		.amdhsa_ieee_mode 1
		.amdhsa_fp16_overflow 0
		.amdhsa_tg_split 0
		.amdhsa_exception_fp_ieee_invalid_op 0
		.amdhsa_exception_fp_denorm_src 0
		.amdhsa_exception_fp_ieee_div_zero 0
		.amdhsa_exception_fp_ieee_overflow 0
		.amdhsa_exception_fp_ieee_underflow 0
		.amdhsa_exception_fp_ieee_inexact 0
		.amdhsa_exception_int_div_zero 0
	.end_amdhsa_kernel

amdhsa.kernels:
  - .agpr_count:     0
    .args:
      - .offset:         0
        .size:           256
        .value_kind:     by_value
      - .offset:         256
        .size:           4
        .value_kind:     hidden_block_count_x
      - .offset:         260
        .size:           4
        .value_kind:     hidden_block_count_y
      - .offset:         264
        .size:           4
        .value_kind:     hidden_block_count_z
      - .offset:         268
        .size:           2
        .value_kind:     hidden_group_size_x
      - .offset:         270
        .size:           2
        .value_kind:     hidden_group_size_y
      - .offset:         272
        .size:           2
        .value_kind:     hidden_group_size_z
      - .offset:         274
        .size:           2
        .value_kind:     hidden_remainder_x
      - .offset:         276
        .size:           2
        .value_kind:     hidden_remainder_y
      - .offset:         278
        .size:           2
        .value_kind:     hidden_remainder_z
      - .offset:         296
        .size:           8
        .value_kind:     hidden_global_offset_x
      - .offset:         304
        .size:           8
        .value_kind:     hidden_global_offset_y
      - .offset:         312
        .size:           8
        .value_kind:     hidden_global_offset_z
      - .offset:         320
        .size:           2
        .value_kind:     hidden_grid_dims
      - .offset:         376
        .size:           4
        .value_kind:     hidden_dynamic_lds_size
    .group_segment_fixed_size: 0
    .kernarg_segment_align: 8
    .kernarg_segment_size: 512
    .language:       OpenCL C
    .language_version:
      - 2
      - 0
    .max_flat_workgroup_size: 512
    .name:           _Z9trunk_fwd4Args
    .private_segment_fixed_size: 0
    .sgpr_count:     108
    .sgpr_spill_count: 204
    .symbol:         _Z9trunk_fwd4Args.kd
    .uniform_work_group_size: 1
    .uses_dynamic_stack: false
    .vgpr_count:     256
    .vgpr_spill_count: 0
    .wavefront_size: 64
